# P6 queue: SSD prompt items pre-assigned so all 24 heads of batch b run on workgroups with bid%8 == b (B/C shared in one XCD L2); dynamic tickets for the rest
# speedup vs baseline: 1.0301x; 1.0301x over previous
.LBB0_1066:
	v_writelane_b32 v251, s36, 50
	v_writelane_b32 v253, s79, 0
	v_writelane_b32 v253, s78, 1
	v_writelane_b32 v251, s37, 51
	v_writelane_b32 v251, s54, 52
	v_writelane_b32 v253, s76, 2
	s_nop 0
	v_writelane_b32 v251, s55, 53
	v_writelane_b32 v253, s77, 3
	v_writelane_b32 v251, s96, 54
	v_writelane_b32 v253, s69, 4
	v_writelane_b32 v251, s97, 55
	v_writelane_b32 v253, s72, 5
	v_writelane_b32 v251, s66, 56
	s_nop 0
	v_writelane_b32 v253, s73, 6
	v_writelane_b32 v251, s67, 57
	v_writelane_b32 v253, s70, 7
	v_writelane_b32 v251, s75, 58
	v_writelane_b32 v251, s74, 59
	v_writelane_b32 v253, s71, 8
	v_writelane_b32 v253, s68, 9
	v_writelane_b32 v251, s59, 60
	v_writelane_b32 v253, s58, 10
	v_writelane_b32 v251, s60, 61
	s_nop 0
	v_writelane_b32 v253, s59, 11
	v_writelane_b32 v251, s61, 62
	v_writelane_b32 v253, s56, 12
	v_writelane_b32 v251, s63, 63
	s_nop 0
	v_writelane_b32 v253, s57, 13
	s_or_b64 exec, exec, s[30:31]
	v_readlane_b32 s0, v251, 10
	s_add_i32 s1, s0, 0xffffe200
	v_writelane_b32 v253, s1, 14
	s_lshl_b32 s1, s0, 8
	s_cmp_gt_u32 s62, 63
	v_writelane_b32 v253, s1, 15
	s_cselect_b64 s[2:3], -1, 0
	v_writelane_b32 v253, s2, 16
	s_cmp_eq_u32 s0, 7
	s_cselect_b64 s[0:1], -1, 0
	v_writelane_b32 v253, s3, 17
	s_add_u32 s56, s40, 0x4a5c000
	v_writelane_b32 v253, s0, 18
	s_addc_u32 s57, s41, 0
	s_mov_b64 s[34:35], s[64:65]
	v_writelane_b32 v253, s1, 19
	s_add_u32 s0, s40, 0x4220000
	v_writelane_b32 v253, s0, 20
	s_addc_u32 s0, s41, 0
	v_writelane_b32 v253, s0, 21
	s_add_i32 s0, 0, 0x22000
	v_writelane_b32 v253, s0, 22
	s_add_i32 s0, 0, 0x11000
	v_writelane_b32 v253, s0, 23
	s_add_i32 s0, 0, 0x19800
	v_writelane_b32 v253, s0, 24
	s_add_i32 s0, 0, 0x1dc00
	v_writelane_b32 v253, s0, 25
	s_add_i32 s0, 0, 0x2643c
	v_writelane_b32 v253, s0, 26
	s_add_i32 s0, 0, 0x2647c
	v_writelane_b32 v253, s0, 27
	s_add_i32 s0, 0, 0x264bc
	v_writelane_b32 v253, s0, 28
	s_add_i32 s0, 0, 0x264fc
	v_writelane_b32 v253, s0, 29
	s_add_i32 s0, 0, 0x2653c
	v_writelane_b32 v253, s0, 30
	s_add_i32 s0, 0, 0x2657c
	v_writelane_b32 v253, s0, 31
	s_add_i32 s0, 0, 0x265bc
	v_writelane_b32 v253, s0, 32
	s_add_i32 s0, 0, 0x265fc
	v_writelane_b32 v253, s0, 33
	v_writelane_b32 v253, s34, 34
	v_readlane_b32 s36, v252, 48
	v_readlane_b32 s42, v252, 54
	v_writelane_b32 v253, s35, 35
	v_readlane_b32 s43, v252, 55
	v_readlane_b32 s48, v252, 60
	v_readlane_b32 s49, v252, 61
	v_readlane_b32 s50, v252, 62
	v_readlane_b32 s51, v252, 63
	v_writelane_b32 v253, s56, 36
	v_mov_b32_e32 v187, 0
	s_add_i32 s76, 0, 0x26a00
	v_readlane_b32 s48, v251, 0
	v_readlane_b32 s42, v251, 37
	v_writelane_b32 v253, s57, 37
	s_mov_b32 s81, 0
	s_movk_i32 s77, 0x2600
	s_movk_i32 s78, 0x1000
	s_mov_b32 s33, 0xbfb8aa3b
	v_mov_b32_e32 v199, 0x3eaaaaab
	s_mov_b32 s58, 0x800000
	s_mov_b32 s59, 0x3f317217
	s_mov_b32 s96, 0x7f800000
	s_mov_b32 s97, 0x3dcccccd
	s_movk_i32 s79, 0x2000
	v_mov_b32_e32 v200, s76
	v_mbcnt_hi_u32_b32 v198, -1, v250
	v_mov_b32_e32 v201, 0x41b17218
	v_mov_b32_e32 v0, v187
	v_mov_b32_e32 v1, v187
	v_mov_b32_e32 v2, v187
	v_mov_b32_e32 v3, v187
	v_bfrev_b32_e32 v202, 0.5
	v_readlane_b32 s37, v252, 49
	v_readlane_b32 s38, v252, 50
	v_readlane_b32 s39, v252, 51
	v_readlane_b32 s40, v252, 52
	v_readlane_b32 s41, v252, 53
	v_readlane_b32 s49, v251, 1
	v_readlane_b32 s50, v251, 2
	v_readlane_b32 s51, v251, 3
	v_readlane_b32 s52, v251, 4
	v_readlane_b32 s53, v251, 5
	v_readlane_b32 s54, v251, 6
	v_readlane_b32 s55, v251, 7
	v_readlane_b32 s43, v251, 38
	v_writelane_b32 v253, s76, 38
	s_waitcnt lgkmcnt(0)
	s_barrier
	v_readlane_b32 s44, v252, 56
	v_readlane_b32 s45, v252, 57
	v_readlane_b32 s46, v252, 58
	v_readlane_b32 s47, v252, 59
	v_readlane_b32 s98, v251, 19
	s_lshr_b32 s98, s98, 3
	s_and_b32 s99, s98, 7
	s_mul_i32 s99, s99, 24
	s_lshr_b32 s100, s98, 3
	s_add_i32 s99, s99, s100
	s_cmpk_lt_u32 s98, 0xc0
	s_cselect_b32 s98, s99, -1
	s_branch .LBB0_1070

.LBB0_1070:
	s_barrier
	s_cmp_lt_i32 s98, 0
	s_cbranch_scc1 .Lq_pop
	v_mov_b32_e32 v4, s98
	s_mov_b32 s98, -1
	s_branch .Lq_have
.Lq_pop:
	s_and_saveexec_b64 s[0:1], s[34:35]
	s_cbranch_execz .LBB0_1074
	s_mov_b64 s[4:5], exec
	v_mbcnt_lo_u32_b32 v4, s4, 0
	v_mbcnt_hi_u32_b32 v4, s5, v4
	v_cmp_eq_u32_e32 vcc, 0, v4
	s_and_saveexec_b64 s[2:3], vcc
	s_cbranch_execz .LBB0_1073
	s_bcnt1_i32_b64 s4, s[4:5]
	v_mov_b32_e32 v5, s4
	global_atomic_add v5, v187, v5, s[54:55] sc0

.LBB0_1074:
	s_or_b64 exec, exec, s[0:1]
	s_waitcnt lgkmcnt(0)
	s_barrier
	ds_read_b32 v4, v200
	s_waitcnt lgkmcnt(0)
	v_add_u32_e32 v4, 0xc0, v4
.Lq_have:
	s_movk_i32 s0, 0x43f
	v_cmp_lt_i32_e32 vcc, s0, v4
	v_readfirstlane_b32 s44, v4
	s_mov_b64 s[0:1], -1
	s_cbranch_vccnz .LBB0_1069
	s_cmpk_gt_i32 s44, 0xbf
	s_cbranch_scc0 .LBB0_1183
	s_cmpk_gt_u32 s44, 0x2bf
	s_cbranch_scc0 .LBB0_1132
	s_cmpk_gt_u32 s44, 0x3bf
	s_cbranch_scc0 .LBB0_1099
	v_mov_b32_e32 v60, v184
	s_lshl_b32 s0, s44, 3
	s_waitcnt vmcnt(0)
	v_ashrrev_i32_e32 v20, 4, v60
	v_readlane_b32 s1, v253, 14
	v_lshlrev_b32_e32 v62, 3, v20
	v_readlane_b32 s2, v251, 27
	s_add_i32 s6, s1, s0
	v_ashrrev_i32_e32 v63, 31, v62
	v_readlane_b32 s3, v251, 28
	s_and_b32 s4, s6, 31
	v_and_b32_e32 v68, 15, v60
	v_cmp_lt_i32_e64 s[0:1], 1, v20
	v_cmp_gt_i32_e32 vcc, 2, v20
	v_lshl_add_u64 v[4:5], v[62:63], 1, s[2:3]
	v_mov_b32_e32 v24, 0
	v_mov_b32_e32 v28, 0
	v_mov_b32_e32 v29, 0
	v_mov_b32_e32 v30, 0
	v_mov_b32_e32 v31, 0
	s_and_saveexec_b64 s[2:3], vcc
	s_cbranch_execz .LBB0_1080
	s_lshl_b32 s5, s4, 12
	v_lshl_or_b32 v186, v68, 5, s5
	v_lshl_add_u64 v[6:7], v[4:5], 0, v[186:187]
	global_load_dwordx4 v[28:31], v[6:7], off
